# attention K/V LDS-DMA addresses: SGPR base + 32-bit per-lane offset (two 32-bit VALU ops instead of a 64-bit mad per piece)
# baseline (speedup 1.0000x reference)
; #define DMAT(kt, so) do { const unsigned rb_ = (unsigned)ROWBASE(kt); _Pragma("unroll") for (int r = 0; r < 3; ++r) if (wid + 8 * r < 22) \
;         __builtin_amdgcn_global_load_lds((const unsigned*)(dsrc[r] + (size_t)rb_ * dmul[r]), (LAS unsigned*)(lds + (so) + dlds[r]), 16, 0, 0); } while (0)
; __device__ __forceinline__ void attn_unit2(LAS unsigned char* lds, const bf16_t* __restrict__ Q, const bf16_t* __restrict__ KN, const bf16_t* __restrict__ KPE, ...
;     ...
;     const int pi = (r32 & 0x13) | ((r32 & 4) << 1) | ((r32 & 8) >> 1);
;     const int ka_off = pi * KROW + hi * 16, va_off = KBUF + r32 * VROW + hi * 16;
;     constexpr int SLOT = KBUF + VBUF;
;     const char* dsrc[3]; unsigned dmul[3]; int dlds[3];
; #pragma unroll
;     for (int r = 0; r < 3; ++r) {
;         const int ii = wid + 8 * r;
;         if (ii < 13) {
;             const int p = 64 * ii + lane, row = p / 13, cc = p % 13;
;             if (cc >= 8 && cc < 12) { dsrc[r] = (const char*)(KPE + (size_t)row * 32 + 8 * (cc - 8)); dmul[r] = 64u; }
;             else { dsrc[r] = (const char*)(KN + (size_t)row * 512 + h * 64 + 8 * (cc == 12 ? 0 : cc)); dmul[r] = 1024u; }
;             dlds[r] = 1024 * ii;
;         } else {
;             const int p = 64 * (ii - 13) + lane, d = p / 9, cc = p % 9;
;             dsrc[r] = (const char*)(VT + (size_t)(h * 64 + (d < 64 ? d : 63)) * MT + 8 * (cc == 8 ? 0 : cc)); dmul[r] = 2u;
;             dlds[r] = KBUF + 1024 * (ii - 13);
;         }
;     }
;     ...
;     DMAT(0, 0);
;     DMAT(1, SLOT);
;     __syncthreads();
;     int sc = 0, sn = SLOT, snn = 2 * SLOT;
;     f32x16 oa0 = {}, oa1 = {}, ob0 = {}, ob1 = {};
;     float ma = -1.0e30f, mb = -1.0e30f, la = 0.f, lb = 0.f;
; __global__ void __launch_bounds__(512, 2) mega_fwd(Args a_byval) {
;     ...
;     unsigned char* ws = a.ws;
.LBB0_354:
	v_and_b32_e32 v0, 19, v3
	v_lshlrev_b32_e32 v1, 1, v3
	v_lshrrev_b32_e32 v3, 1, v3
	v_and_b32_e32 v1, 8, v1
	v_and_b32_e32 v3, 4, v3
	v_or3_b32 v0, v0, v1, v3
	v_mov_b32_e32 v16, v129
	v_mov_b32_e32 v17, v129
	v_mov_b32_e32 v30, v129
	v_mov_b32_e32 v31, v129
	v_mul_u32_u24_e32 v183, 0xd0, v0
	v_mul_u32_u24_e32 v187, 0x90, v2
	v_mov_b32_e32 v18, v129
	v_mov_b32_e32 v19, v129
	v_mov_b32_e32 v20, v129
	v_mov_b32_e32 v21, v129
	v_mov_b32_e32 v22, v129
	v_mov_b32_e32 v23, v129
	v_mov_b32_e32 v24, v129
	v_mov_b32_e32 v25, v129
	v_mov_b32_e32 v26, v129
	v_mov_b32_e32 v27, v129
	v_mov_b32_e32 v28, v129
	v_mov_b32_e32 v29, v129
	v_mov_b64_e32 v[62:63], v[30:31]
	v_mov_b64_e32 v[46:47], v[30:31]
	v_mov_b64_e32 v[0:1], v[16:17]
	s_add_i32 s10, s14, 0x4080
	s_add_i32 s11, s24, 0xffffff80
	s_mov_b32 s24, 0
	v_mov_b32_e32 v191, 0
	v_mov_b32_e32 v194, 0xf149f2ca
	s_mov_b32 s25, 0xb000
	s_movk_i32 s26, 0x5800
	s_mov_b32 s14, 0
	v_mov_b64_e32 v[60:61], v[28:29]
	v_mov_b64_e32 v[58:59], v[26:27]
	v_mov_b64_e32 v[56:57], v[24:25]
	v_mov_b64_e32 v[54:55], v[22:23]
	v_mov_b64_e32 v[52:53], v[20:21]
	v_mov_b64_e32 v[50:51], v[18:19]
	v_mov_b64_e32 v[48:49], v[16:17]
	v_mov_b64_e32 v[44:45], v[28:29]
	v_mov_b64_e32 v[42:43], v[26:27]
	v_mov_b64_e32 v[40:41], v[24:25]
	v_mov_b64_e32 v[38:39], v[22:23]
	v_mov_b64_e32 v[36:37], v[20:21]
	v_mov_b64_e32 v[34:35], v[18:19]
	v_mov_b64_e32 v[32:33], v[16:17]
	v_mov_b64_e32 v[2:3], v[18:19]
	v_mov_b64_e32 v[4:5], v[20:21]
	v_mov_b64_e32 v[6:7], v[22:23]
	v_mov_b64_e32 v[8:9], v[24:25]
	v_mov_b64_e32 v[10:11], v[26:27]
	v_mov_b64_e32 v[12:13], v[28:29]
	v_mov_b64_e32 v[14:15], v[30:31]
	v_mov_b32_e32 v195, 0xf149f2ca
	v_mov_b32_e32 v193, 0
	s_mov_b32 s27, 0
	s_waitcnt vmcnt(0) lgkmcnt(0)
	s_barrier
	s_mov_b32 s34, s14
	v_readlane_b32 s98, v255, 12
	v_readlane_b32 s99, v255, 13
	s_nop 3
	s_load_dwordx2 s[98:99], s[98:99], 0xa0
	s_waitcnt lgkmcnt(0)
	v_readlane_b32 s15, v255, 15
	s_nop 3
	s_cmp_lt_u32 s15, 4
	s_cbranch_scc1 .Lat_noprio
	s_setprio 1

; #define LAS __attribute__((address_space(3)))
; __device__ __forceinline__ void attn_unit2(LAS unsigned char* lds, const bf16_t* __restrict__ Q, const bf16_t* __restrict__ KN, const bf16_t* __restrict__ KPE, ...
;     ...
;         SOFTMAX2(sa0, sa1, ma, la, oa0, oa1, pa);
;         SOFTMAX2(sb0, sb1, mb, lb, ob0, ob1, pb);
;     ...
;         const LAS unsigned char* va = lds + sc + va_off;
; #pragma unroll
;         for (int st = 0; st < 4; ++st) {
;             const bf16x8 v0 = *(const LAS bf16x8*)(va + st * 32);
;             const bf16x8 v1 = *(const LAS bf16x8*)(va + 32 * VROW + st * 32);
;             const bf16x8 fa = __builtin_bit_cast(bf16x8, pa[st]), fb = __builtin_bit_cast(bf16x8, pb[st]);
;             oa0 = __builtin_amdgcn_mfma_f32_32x32x16_bf16(v0, fa, oa0, 0, 0, 0);
;             oa1 = __builtin_amdgcn_mfma_f32_32x32x16_bf16(v1, fa, oa1, 0, 0, 0);
;             ob0 = __builtin_amdgcn_mfma_f32_32x32x16_bf16(v0, fb, ob0, 0, 0, 0);
;             ob1 = __builtin_amdgcn_mfma_f32_32x32x16_bf16(v1, fb, ob1, 0, 0, 0);
;         }
;         __builtin_amdgcn_sched_barrier(0);
;         __syncthreads();
.Lat_back_bE:
	v_add_f32_e32 v193, v193, v230
	v_cvt_pk_bf16_f32 v80, v80, v81
	v_cvt_pk_bf16_f32 v81, v82, v83
	v_mfma_f32_32x32x16_bf16 v[112:127], v[220:223], v[174:177], v[112:127]
	v_cvt_pk_bf16_f32 v82, v84, v85
	v_cvt_pk_bf16_f32 v83, v86, v87
	v_cvt_pk_bf16_f32 v84, v88, v89
	v_mfma_f32_32x32x16_bf16 v[112:127], v[240:243], v[248:251], v[112:127]
	v_cvt_pk_bf16_f32 v85, v90, v91
	v_cvt_pk_bf16_f32 v86, v92, v93
	v_cvt_pk_bf16_f32 v87, v94, v95
	s_waitcnt vmcnt(0)
	s_barrier
	s_cmp_lt_u32 s27, 2
	s_cselect_b32 s14, s10, s11
	s_add_i32 s14, s14, s24
	v_add3_u32 v224, s26, v183, v128
	ds_read_b128 v[212:215], v224 offset:0
	ds_read_b128 v[216:219], v224 offset:32
	ds_read_b128 v[220:223], v224 offset:64
	v_mfma_f32_32x32x16_bf16 v[16:31], v[196:199], v[64:67], v[16:31]
	v_exp_f32_e32 v96, v96
	v_exp_f32_e32 v97, v97
	s_cmpk_gt_u32 s27, 0x81
	s_cbranch_scc1 .Lat_dmaL_0
	s_and_b64 vcc, exec, s[4:5]
	s_cbranch_vccnz .Lat_dmaL_0
	v_mad_u32_u24 v234, v182, s14, v180
	v_subrev_u32_e32 v234, s98, v234
	s_add_i32 m0, s25, s19
	s_nop 0
	global_load_lds_dwordx4 v234, s[98:99]
.Lat_dmaL_0:
	v_exp_f32_e32 v98, v98
	v_exp_f32_e32 v99, v99
	v_mfma_f32_32x32x16_bf16 v[48:63], v[200:203], v[64:67], v[48:63]
	v_exp_f32_e32 v100, v100
	v_exp_f32_e32 v101, v101
	s_cmpk_gt_u32 s27, 0x81
	s_cbranch_scc1 .Lat_dmaL_1
	s_and_b64 vcc, exec, s[6:7]
	s_cbranch_vccnz .Lat_dmaL_1
	v_mad_u32_u24 v234, v186, s14, v184
	v_subrev_u32_e32 v234, s98, v234
	s_add_i32 m0, s25, s20
	s_nop 0
	global_load_lds_dwordx4 v234, s[98:99]
.Lat_dmaL_1:
	v_add_f32_e32 v230, v96, v97
	v_exp_f32_e32 v102, v102
	v_mfma_f32_32x32x16_bf16 v[16:31], v[204:207], v[68:71], v[16:31]
	v_exp_f32_e32 v103, v103
	v_add_f32_e32 v231, v98, v99
	s_cmpk_gt_u32 s27, 0x81
	s_cbranch_scc1 .Lat_dmaL_2
	s_and_b64 vcc, exec, s[8:9]
	s_cbranch_vccnz .Lat_dmaL_2
	v_mad_u32_u24 v234, v190, s14, v188
	v_subrev_u32_e32 v234, s98, v234
	s_add_i32 m0, s25, s21
	s_nop 0
	global_load_lds_dwordx4 v234, s[98:99]
